# P0 x-row f32 loads non-temporal as well
# speedup vs baseline: 1.0175x; 1.0085x over previous
; #define LAS __attribute__((address_space(3)))
; __device__ __forceinline__ float wave_sum(float v) { for (int o = 32; o >= 1; o >>= 1) v += __shfl_xor(v, o); return v; }
; __device__ __forceinline__ u32x2 pk4(f32x4 v) { u32x2 w; w.x = cvt_pk_bf16(v[0], v[1]); w.y = cvt_pk_bf16(v[2], v[3]); return w; }
; __device__ __forceinline__ void p0_rows(const Args& a, LAS unsigned char* lds, int gw, int NGW, int wave, int lane, int tid) {
;     ...
;     for (int idx = tid; idx < 1024 * 16; idx += 512) { const int k = idx >> 4, j = idx & 15; WdL[(k >> 8) * 4112 + (k & 255) * 16 + j] = a.in[I_WIN][(size_t)k * DIN + 4608 + j]; }
;     __syncthreads();
;     bf16_t* H = (bf16_t*)((unsigned char*)a.out + Y_H); float* DLR = (float*)((unsigned char*)a.out + Y_DLR);
;     const f32x4* gp = (const f32x4*)a.in[I_NMPRE] + lane; f32x4 g[4];
; #pragma unroll
;     for (int j = 0; j < 4; ++j) g[j] = gp[64 * j];
;     for (int row = gw; row < MT; row += NGW) {
;         const f32x4* xr = (const f32x4*)xrow_ptr(a, row) + lane; f32x4 v[4]; float s = 0.f;
; #pragma unroll
;         for (int j = 0; j < 4; ++j) { v[j] = xr[64 * j]; s += (v[j][0] * v[j][0] + v[j][1] * v[j][1]) + (v[j][2] * v[j][2] + v[j][3] * v[j][3]); }
;         const float rstd = rsqrtf(wave_sum(s) * (1.f / DM) + EPS);
;         u32x2* ho = (u32x2*)(H + (size_t)row * DM) + lane;
; #pragma unroll
;         for (int j = 0; j < 4; ++j) { v[j] = v[j] * rstd * g[j]; ho[64 * j] = pk4(v[j]); *(LAS f32x4*)(hrow + j * 264 + 4 * lane) = v[j]; }
.LBB0_129:
	s_cmpk_lg_i32 s58, 0x100
	s_cbranch_scc1 .Lp0m_generic
	v_lshlrev_b32_e32 v28, 4, v176
	v_lshlrev_b32_e32 v29, 3, v176
	v_mov_b32_e32 v16, 0x358637bd
	v_mov_b32_e32 v17, v28
	v_and_b32_e32 v30, 15, v176
	v_lshrrev_b32_e32 v31, 4, v176
	v_readlane_b32 s36, v252, 1
	v_readlane_b32 s37, v252, 2
	v_readlane_b32 s38, v252, 3
	v_readlane_b32 s39, v252, 4
	v_readlane_b32 s46, v252, 11
	v_readlane_b32 s47, v252, 12
	s_mov_b32 s3, 0x800000
	s_mul_i32 s42, s93, 0x1010
	s_nop 4
	global_load_dwordx4 v[0:3], v28, s[46:47]
	global_load_dwordx4 v[4:7], v28, s[46:47] offset:1024
	global_load_dwordx4 v[8:11], v28, s[46:47] offset:2048
	global_load_dwordx4 v[12:15], v28, s[46:47] offset:3072
	s_lshl_b32 s10, s81, 12
	s_add_u32 s44, s36, s10
	s_addc_u32 s45, s37, 0
	global_load_dwordx4 v[32:35], v28, s[44:45] nt
	global_load_dwordx4 v[36:39], v28, s[44:45] offset:1024 nt
	global_load_dwordx4 v[40:43], v28, s[44:45] offset:2048 nt
	global_load_dwordx4 v[44:47], v28, s[44:45] offset:3072 nt
	s_add_u32 s10, s44, 0x800000
	s_addc_u32 s11, s45, 0
	global_load_dwordx4 v[48:51], v28, s[10:11] nt
	global_load_dwordx4 v[52:55], v28, s[10:11] offset:1024 nt
	global_load_dwordx4 v[56:59], v28, s[10:11] offset:2048 nt
	global_load_dwordx4 v[60:63], v28, s[10:11] offset:3072 nt
	s_lshl_b32 s10, s81, 11
	s_add_u32 s40, s52, s10
	s_addc_u32 s41, s53, 0
	v_lshlrev_b32_e32 v24, 8, v31
	s_lshl_b32 s10, s93, 5
	v_add_u32_e32 v24, s10, v24
	v_mul_u32_u24_e32 v24, 0x1a10, v24
	v_add_u32_e32 v24, v24, v30
	v_add_u32_e32 v24, 0x1200, v24
	v_lshlrev_b32_e32 v24, 2, v24
	s_mov_b64 s[0:1], s[14:15]
	global_load_dword v96, v24, s[0:1]
	s_add_u32 s0, s0, 0x6840
	s_addc_u32 s1, s1, 0
	global_load_dword v97, v24, s[0:1]
	s_add_u32 s0, s0, 0x6840
	s_addc_u32 s1, s1, 0
	global_load_dword v98, v24, s[0:1]
	s_add_u32 s0, s0, 0x6840
	s_addc_u32 s1, s1, 0
	global_load_dword v99, v24, s[0:1]
	s_add_u32 s0, s0, 0x6840
	s_addc_u32 s1, s1, 0
	global_load_dword v100, v24, s[0:1]
	s_add_u32 s0, s0, 0x6840
	s_addc_u32 s1, s1, 0
	global_load_dword v101, v24, s[0:1]
	s_add_u32 s0, s0, 0x6840
	s_addc_u32 s1, s1, 0
	global_load_dword v102, v24, s[0:1]
	s_add_u32 s0, s0, 0x6840
	s_addc_u32 s1, s1, 0
	global_load_dword v103, v24, s[0:1]
	s_add_u32 s0, s0, 0x6840
	s_addc_u32 s1, s1, 0
	global_load_dword v104, v24, s[0:1]
	s_add_u32 s0, s0, 0x6840
	s_addc_u32 s1, s1, 0
	global_load_dword v105, v24, s[0:1]
	s_add_u32 s0, s0, 0x6840
	s_addc_u32 s1, s1, 0
	global_load_dword v106, v24, s[0:1]
	s_add_u32 s0, s0, 0x6840
	s_addc_u32 s1, s1, 0
	global_load_dword v107, v24, s[0:1]
	s_add_u32 s0, s0, 0x6840
	s_addc_u32 s1, s1, 0
	global_load_dword v108, v24, s[0:1]
	s_add_u32 s0, s0, 0x6840
	s_addc_u32 s1, s1, 0
	global_load_dword v109, v24, s[0:1]
	s_add_u32 s0, s0, 0x6840
	s_addc_u32 s1, s1, 0
	global_load_dword v110, v24, s[0:1]
	s_add_u32 s0, s0, 0x6840
	s_addc_u32 s1, s1, 0
	global_load_dword v111, v24, s[0:1]
	s_add_u32 s0, s0, 0x6840
	s_addc_u32 s1, s1, 0
	global_load_dword v112, v24, s[0:1]
	s_add_u32 s0, s0, 0x6840
	s_addc_u32 s1, s1, 0
	global_load_dword v113, v24, s[0:1]
	s_add_u32 s0, s0, 0x6840
	s_addc_u32 s1, s1, 0
	global_load_dword v114, v24, s[0:1]
	s_add_u32 s0, s0, 0x6840
	s_addc_u32 s1, s1, 0
	global_load_dword v115, v24, s[0:1]
	s_add_u32 s0, s0, 0x6840
	s_addc_u32 s1, s1, 0
	global_load_dword v116, v24, s[0:1]
	s_add_u32 s0, s0, 0x6840
	s_addc_u32 s1, s1, 0
	global_load_dword v117, v24, s[0:1]
	s_add_u32 s0, s0, 0x6840
	s_addc_u32 s1, s1, 0
	global_load_dword v118, v24, s[0:1]
	s_add_u32 s0, s0, 0x6840
	s_addc_u32 s1, s1, 0
	global_load_dword v119, v24, s[0:1]
	s_add_u32 s0, s0, 0x6840
	s_addc_u32 s1, s1, 0
	global_load_dword v120, v24, s[0:1]
	s_add_u32 s0, s0, 0x6840
	s_addc_u32 s1, s1, 0
	global_load_dword v121, v24, s[0:1]
	s_add_u32 s0, s0, 0x6840
	s_addc_u32 s1, s1, 0
	global_load_dword v122, v24, s[0:1]
	s_add_u32 s0, s0, 0x6840
	s_addc_u32 s1, s1, 0
	global_load_dword v123, v24, s[0:1]
	s_add_u32 s0, s0, 0x6840
	s_addc_u32 s1, s1, 0
	global_load_dword v124, v24, s[0:1]
	s_add_u32 s0, s0, 0x6840
	s_addc_u32 s1, s1, 0
	global_load_dword v125, v24, s[0:1]
	s_add_u32 s0, s0, 0x6840
	s_addc_u32 s1, s1, 0
	global_load_dword v126, v24, s[0:1]
	s_add_u32 s0, s0, 0x6840
	s_addc_u32 s1, s1, 0
	global_load_dword v127, v24, s[0:1]
	v_mul_u32_u24_e32 v19, 0x1010, v30
	v_lshlrev_b32_e32 v25, 10, v31
	s_lshl_b32 s10, s93, 7
	v_add3_u32 v19, v19, v25, s10
	v_add_u32_e32 v20, 0x10100, v19
	s_lshl_b32 s10, s93, 10
	s_add_i32 s10, s10, 0x20200
	v_add_u32_e32 v21, s10, v28
	v_and_b32_e32 v25, 3, v31
	s_lshl_b32 s10, s93, 8
	s_add_i32 s10, s10, 0x20200
	v_lshlrev_b32_e32 v22, 4, v30
	v_lshl_add_u32 v22, v25, 2, v22
	v_add_u32_e32 v22, s10, v22
	s_lshl_b32 s10, s93, 2
	v_add_u32_e32 v26, s10, v25
	v_and_b32_e32 v27, 7, v26
	v_lshrrev_b32_e32 v26, 3, v26
	v_lshl_add_u32 v27, v26, 11, v27
	s_lshl_b32 s10, s2, 3
	v_add_u32_e32 v27, s10, v27
	v_lshlrev_b32_e32 v27, 6, v27
	v_lshl_add_u32 v23, v30, 2, v27
	v_add_u32_e32 v23, 0x4000000, v23
	s_waitcnt lgkmcnt(0)
	s_barrier
; #define LAS __attribute__((address_space(3)))
; __device__ __forceinline__ float wave_sum(float v) { for (int o = 32; o >= 1; o >>= 1) v += __shfl_xor(v, o); return v; }
; __device__ __forceinline__ u32x2 pk4(f32x4 v) { u32x2 w; w.x = cvt_pk_bf16(v[0], v[1]); w.y = cvt_pk_bf16(v[2], v[3]); return w; }
; __device__ __forceinline__ void p0_rows(const Args& a, LAS unsigned char* lds, int gw, int NGW, int wave, int lane, int tid) {
;     ...
;         const f32x4* xr = (const f32x4*)xrow_ptr(a, row) + lane; f32x4 v[4]; float s = 0.f;
; #pragma unroll
;         for (int j = 0; j < 4; ++j) { v[j] = xr[64 * j]; s += (v[j][0] * v[j][0] + v[j][1] * v[j][1]) + (v[j][2] * v[j][2] + v[j][3] * v[j][3]); }
;         const float rstd = rsqrtf(wave_sum(s) * (1.f / DM) + EPS);
;         u32x2* ho = (u32x2*)(H + (size_t)row * DM) + lane;
; #pragma unroll
;         for (int j = 0; j < 4; ++j) { v[j] = v[j] * rstd * g[j]; ho[64 * j] = pk4(v[j]); *(LAS f32x4*)(hrow + j * 264 + 4 * lane) = v[j]; }
	s_add_u32 s44, s44, 0x1000000
	s_addc_u32 s45, s45, 0
	global_load_dwordx4 v[192:195], v28, s[44:45] nt
	global_load_dwordx4 v[196:199], v28, s[44:45] offset:1024 nt
	global_load_dwordx4 v[200:203], v28, s[44:45] offset:2048 nt
	global_load_dwordx4 v[204:207], v28, s[44:45] offset:3072 nt
	s_add_u32 s10, s44, 0x800000
	s_addc_u32 s11, s45, 0
	global_load_dwordx4 v[208:211], v28, s[10:11] nt
	global_load_dwordx4 v[212:215], v28, s[10:11] offset:1024 nt
	global_load_dwordx4 v[216:219], v28, s[10:11] offset:2048 nt
	global_load_dwordx4 v[220:223], v28, s[10:11] offset:3072 nt
	s_waitcnt vmcnt(40)
	v_mul_f32_e32 v64, v32, v32
	v_fmac_f32_e32 v64, v33, v33
	v_mul_f32_e32 v65, v34, v34
	v_fmac_f32_e32 v65, v35, v35
	v_add_f32_e32 v64, v64, v65
	v_mul_f32_e32 v66, v36, v36
	v_fmac_f32_e32 v66, v37, v37
	v_mul_f32_e32 v67, v38, v38
	v_fmac_f32_e32 v67, v39, v39
	v_add_f32_e32 v66, v66, v67
	v_mul_f32_e32 v68, v40, v40
	v_fmac_f32_e32 v68, v41, v41
	v_mul_f32_e32 v69, v42, v42
	v_fmac_f32_e32 v69, v43, v43
	v_add_f32_e32 v68, v68, v69
	v_mul_f32_e32 v70, v44, v44
	v_fmac_f32_e32 v70, v45, v45
	v_mul_f32_e32 v71, v46, v46
	v_fmac_f32_e32 v71, v47, v47
	v_add_f32_e32 v70, v70, v71
	v_add_f32_e32 v64, v64, v66
	v_add_f32_e32 v64, v64, v68
	v_add_f32_e32 v64, v64, v70
	s_nop 1
	v_add_f32_dpp v88, v64, v64 quad_perm:[1,0,3,2] row_mask:0xf bank_mask:0xf
	s_nop 1
	v_add_f32_dpp v88, v88, v88 quad_perm:[2,3,0,1] row_mask:0xf bank_mask:0xf
	s_nop 1
	v_add_f32_dpp v88, v88, v88 row_half_mirror row_mask:0xf bank_mask:0xf
	s_nop 1
	v_add_f32_dpp v88, v88, v88 row_mirror row_mask:0xf bank_mask:0xf
	s_nop 1
	v_readlane_b32 s48, v88, 0
	v_readlane_b32 s49, v88, 16
	v_readlane_b32 s50, v88, 32
	v_readlane_b32 s51, v88, 48
	s_nop 1
	v_mov_b32_e32 v88, s48
	v_add_f32_e32 v88, s49, v88
	v_add_f32_e32 v88, s50, v88
	v_add_f32_e32 v88, s51, v88
	v_fmamk_f32 v88, v88, 0x3a800000, v16
	v_mul_f32_e32 v89, 0x4b800000, v88
	v_cmp_gt_f32_e64 s[8:9], s3, v88
	s_nop 1
	v_cndmask_b32_e64 v88, v88, v89, s[8:9]
	v_rsq_f32_e32 v88, v88
	s_nop 0
	v_mul_f32_e32 v89, 0x45800000, v88
	v_cndmask_b32_e64 v88, v88, v89, s[8:9]
	v_mul_f32_e32 v32, v32, v88
	v_mul_f32_e32 v33, v33, v88
	v_mul_f32_e32 v34, v34, v88
	v_mul_f32_e32 v35, v35, v88
	v_mul_f32_e32 v36, v36, v88
	v_mul_f32_e32 v37, v37, v88
	v_mul_f32_e32 v38, v38, v88
	v_mul_f32_e32 v39, v39, v88
	v_mul_f32_e32 v40, v40, v88
	v_mul_f32_e32 v41, v41, v88
	v_mul_f32_e32 v42, v42, v88
	v_mul_f32_e32 v43, v43, v88
	v_mul_f32_e32 v44, v44, v88
	v_mul_f32_e32 v45, v45, v88
	v_mul_f32_e32 v46, v46, v88
	v_mul_f32_e32 v47, v47, v88
	v_mul_f32_e32 v32, v0, v32
	v_mul_f32_e32 v33, v1, v33
	v_mul_f32_e32 v34, v2, v34
	v_mul_f32_e32 v35, v3, v35
	v_mul_f32_e32 v36, v4, v36
	v_mul_f32_e32 v37, v5, v37
	v_mul_f32_e32 v38, v6, v38
	v_mul_f32_e32 v39, v7, v39
	v_mul_f32_e32 v40, v8, v40
	v_mul_f32_e32 v41, v9, v41
	v_mul_f32_e32 v42, v10, v42
	v_mul_f32_e32 v43, v11, v43
	v_mul_f32_e32 v44, v12, v44
	v_mul_f32_e32 v45, v13, v45
	v_mul_f32_e32 v46, v14, v46
	v_mul_f32_e32 v47, v15, v47
	s_add_i32 s7, s42, 0
	v_add_u32_e32 v18, s7, v17
	ds_write_b128 v18, v[32:35]
	ds_write_b128 v18, v[36:39] offset:1024
	ds_write_b128 v18, v[40:43] offset:2048
	ds_write_b128 v18, v[44:47] offset:3072
	v_cvt_pk_bf16_f32 v80, v32, v33
	v_cvt_pk_bf16_f32 v81, v34, v35
	v_cvt_pk_bf16_f32 v82, v36, v37
	v_cvt_pk_bf16_f32 v83, v38, v39
	v_cvt_pk_bf16_f32 v84, v40, v41
	v_cvt_pk_bf16_f32 v85, v42, v43
	v_cvt_pk_bf16_f32 v86, v44, v45
	v_cvt_pk_bf16_f32 v87, v46, v47
	global_store_dwordx2 v29, v[80:81], s[40:41]
	global_store_dwordx2 v29, v[82:83], s[40:41] offset:512
	global_store_dwordx2 v29, v[84:85], s[40:41] offset:1024
	global_store_dwordx2 v29, v[86:87], s[40:41] offset:1536
	v_mul_f32_e32 v64, v48, v48
	v_fmac_f32_e32 v64, v49, v49
	v_mul_f32_e32 v65, v50, v50
	v_fmac_f32_e32 v65, v51, v51
	v_add_f32_e32 v64, v64, v65
	v_mul_f32_e32 v66, v52, v52
	v_fmac_f32_e32 v66, v53, v53
	v_mul_f32_e32 v67, v54, v54
	v_fmac_f32_e32 v67, v55, v55
	v_add_f32_e32 v66, v66, v67
	v_mul_f32_e32 v68, v56, v56
	v_fmac_f32_e32 v68, v57, v57
	v_mul_f32_e32 v69, v58, v58
	v_fmac_f32_e32 v69, v59, v59
	v_add_f32_e32 v68, v68, v69
	v_mul_f32_e32 v70, v60, v60
	v_fmac_f32_e32 v70, v61, v61
	v_mul_f32_e32 v71, v62, v62
	v_fmac_f32_e32 v71, v63, v63
	v_add_f32_e32 v70, v70, v71
	v_add_f32_e32 v64, v64, v66
	v_add_f32_e32 v64, v64, v68
	v_add_f32_e32 v64, v64, v70
	s_nop 1
	v_add_f32_dpp v88, v64, v64 quad_perm:[1,0,3,2] row_mask:0xf bank_mask:0xf
	s_nop 1
	v_add_f32_dpp v88, v88, v88 quad_perm:[2,3,0,1] row_mask:0xf bank_mask:0xf
	s_nop 1
	v_add_f32_dpp v88, v88, v88 row_half_mirror row_mask:0xf bank_mask:0xf
	s_nop 1
	v_add_f32_dpp v88, v88, v88 row_mirror row_mask:0xf bank_mask:0xf
	s_nop 1
	v_readlane_b32 s48, v88, 0
	v_readlane_b32 s49, v88, 16
	v_readlane_b32 s50, v88, 32
	v_readlane_b32 s51, v88, 48
	s_nop 1
	v_mov_b32_e32 v88, s48
	v_add_f32_e32 v88, s49, v88
	v_add_f32_e32 v88, s50, v88
	v_add_f32_e32 v88, s51, v88
	v_fmamk_f32 v88, v88, 0x3a800000, v16
	v_mul_f32_e32 v89, 0x4b800000, v88
	v_cmp_gt_f32_e64 s[8:9], s3, v88
	s_nop 1
	v_cndmask_b32_e64 v88, v88, v89, s[8:9]
	v_rsq_f32_e32 v88, v88
	s_nop 0
	v_mul_f32_e32 v89, 0x45800000, v88
	v_cndmask_b32_e64 v88, v88, v89, s[8:9]
	v_mul_f32_e32 v48, v48, v88
	v_mul_f32_e32 v49, v49, v88
	v_mul_f32_e32 v50, v50, v88
	v_mul_f32_e32 v51, v51, v88
	v_mul_f32_e32 v52, v52, v88
	v_mul_f32_e32 v53, v53, v88
	v_mul_f32_e32 v54, v54, v88
	v_mul_f32_e32 v55, v55, v88
	v_mul_f32_e32 v56, v56, v88
	v_mul_f32_e32 v57, v57, v88
	v_mul_f32_e32 v58, v58, v88
	v_mul_f32_e32 v59, v59, v88
	v_mul_f32_e32 v60, v60, v88
	v_mul_f32_e32 v61, v61, v88
	v_mul_f32_e32 v62, v62, v88
	v_mul_f32_e32 v63, v63, v88
	v_mul_f32_e32 v48, v0, v48
	v_mul_f32_e32 v49, v1, v49
	v_mul_f32_e32 v50, v2, v50
	v_mul_f32_e32 v51, v3, v51
	v_mul_f32_e32 v52, v4, v52
	v_mul_f32_e32 v53, v5, v53
	v_mul_f32_e32 v54, v6, v54
	v_mul_f32_e32 v55, v7, v55
	v_mul_f32_e32 v56, v8, v56
	v_mul_f32_e32 v57, v9, v57
	v_mul_f32_e32 v58, v10, v58
	v_mul_f32_e32 v59, v11, v59
	v_mul_f32_e32 v60, v12, v60
	v_mul_f32_e32 v61, v13, v61
	v_mul_f32_e32 v62, v14, v62
	v_mul_f32_e32 v63, v15, v63
	s_add_i32 s7, s42, 32896
	v_add_u32_e32 v18, s7, v17
	ds_write_b128 v18, v[48:51]
	ds_write_b128 v18, v[52:55] offset:1024
	ds_write_b128 v18, v[56:59] offset:2048
	ds_write_b128 v18, v[60:63] offset:3072
	s_add_u32 s10, s40, 0x400000
	s_addc_u32 s11, s41, 0
	v_cvt_pk_bf16_f32 v80, v48, v49
	v_cvt_pk_bf16_f32 v81, v50, v51
	v_cvt_pk_bf16_f32 v82, v52, v53
	v_cvt_pk_bf16_f32 v83, v54, v55
	v_cvt_pk_bf16_f32 v84, v56, v57
	v_cvt_pk_bf16_f32 v85, v58, v59
	v_cvt_pk_bf16_f32 v86, v60, v61
	v_cvt_pk_bf16_f32 v87, v62, v63
	global_store_dwordx2 v29, v[80:81], s[10:11]
	global_store_dwordx2 v29, v[82:83], s[10:11] offset:512
	global_store_dwordx2 v29, v[84:85], s[10:11] offset:1024
	global_store_dwordx2 v29, v[86:87], s[10:11] offset:1536
	s_add_u32 s40, s40, 0x800000
	s_addc_u32 s41, s41, 0
	s_waitcnt lgkmcnt(0)
	s_barrier
; #define LAS __attribute__((address_space(3)))
; __device__ __forceinline__ void p0_rows(const Args& a, LAS unsigned char* lds, int gw, int NGW, int wave, int lane, int tid) {
;     ...
;         const f32x4* xr = (const f32x4*)xrow_ptr(a, row) + lane; f32x4 v[4]; float s = 0.f;
; #pragma unroll
;         for (int j = 0; j < 4; ++j) { v[j] = xr[64 * j]; s += (v[j][0] * v[j][0] + v[j][1] * v[j][1]) + (v[j][2] * v[j][2] + v[j][3] * v[j][3]); }
;     ...
;         const int jj = lane & 15, p = lane >> 4; float acc = 0.f;
;         const LAS float* hp = hrow + p * 264; const LAS float* wp = WdL + p * 4112 + jj;
; #pragma unroll 8
;         for (int kk = 0; kk < 256; ++kk) acc += hp[kk] * wp[kk * 16];
;         acc += __shfl_xor(acc, 16); acc += __shfl_xor(acc, 32);
;         if (lane < 16) DLR[(size_t)row * 16 + jj] = acc;
	s_waitcnt vmcnt(16)
	ds_read_b128 v[128:131], v19
	ds_read_b128 v[132:135], v19 offset:16
	ds_read_b128 v[136:139], v19 offset:32
	ds_read_b128 v[140:143], v19 offset:48
	ds_read_b128 v[144:147], v19 offset:64
	ds_read_b128 v[148:151], v19 offset:80
	ds_read_b128 v[152:155], v19 offset:96
	ds_read_b128 v[156:159], v19 offset:112
	s_waitcnt lgkmcnt(7)
	v_mfma_f32_16x16x4_f32 v[160:163], v128, v96, 0
	v_mfma_f32_16x16x4_f32 v[164:167], v129, v97, 0
	v_mfma_f32_16x16x4_f32 v[160:163], v130, v98, v[160:163]
	v_mfma_f32_16x16x4_f32 v[164:167], v131, v99, v[164:167]
	s_waitcnt lgkmcnt(6)
	v_mfma_f32_16x16x4_f32 v[160:163], v132, v100, v[160:163]
	v_mfma_f32_16x16x4_f32 v[164:167], v133, v101, v[164:167]
	v_mfma_f32_16x16x4_f32 v[160:163], v134, v102, v[160:163]
	v_mfma_f32_16x16x4_f32 v[164:167], v135, v103, v[164:167]
	s_waitcnt lgkmcnt(5)
	v_mfma_f32_16x16x4_f32 v[160:163], v136, v104, v[160:163]
	v_mfma_f32_16x16x4_f32 v[164:167], v137, v105, v[164:167]
	v_mfma_f32_16x16x4_f32 v[160:163], v138, v106, v[160:163]
	v_mfma_f32_16x16x4_f32 v[164:167], v139, v107, v[164:167]
	s_waitcnt lgkmcnt(4)
	v_mfma_f32_16x16x4_f32 v[160:163], v140, v108, v[160:163]
	v_mfma_f32_16x16x4_f32 v[164:167], v141, v109, v[164:167]
	v_mfma_f32_16x16x4_f32 v[160:163], v142, v110, v[160:163]
	v_mfma_f32_16x16x4_f32 v[164:167], v143, v111, v[164:167]
	s_waitcnt lgkmcnt(3)
	v_mfma_f32_16x16x4_f32 v[160:163], v144, v112, v[160:163]
	v_mfma_f32_16x16x4_f32 v[164:167], v145, v113, v[164:167]
	v_mfma_f32_16x16x4_f32 v[160:163], v146, v114, v[160:163]
	v_mfma_f32_16x16x4_f32 v[164:167], v147, v115, v[164:167]
	s_waitcnt lgkmcnt(2)
	v_mfma_f32_16x16x4_f32 v[160:163], v148, v116, v[160:163]
	v_mfma_f32_16x16x4_f32 v[164:167], v149, v117, v[164:167]
	v_mfma_f32_16x16x4_f32 v[160:163], v150, v118, v[160:163]
	v_mfma_f32_16x16x4_f32 v[164:167], v151, v119, v[164:167]
	s_waitcnt lgkmcnt(1)
	v_mfma_f32_16x16x4_f32 v[160:163], v152, v120, v[160:163]
	v_mfma_f32_16x16x4_f32 v[164:167], v153, v121, v[164:167]
	v_mfma_f32_16x16x4_f32 v[160:163], v154, v122, v[160:163]
	v_mfma_f32_16x16x4_f32 v[164:167], v155, v123, v[164:167]
	s_waitcnt lgkmcnt(0)
	v_mfma_f32_16x16x4_f32 v[160:163], v156, v124, v[160:163]
	v_mfma_f32_16x16x4_f32 v[164:167], v157, v125, v[164:167]
	v_mfma_f32_16x16x4_f32 v[160:163], v158, v126, v[160:163]
	v_mfma_f32_16x16x4_f32 v[164:167], v159, v127, v[164:167]
	s_nop 9
	v_add_f32_e32 v160, v160, v164
	v_add_f32_e32 v161, v161, v165
	v_add_f32_e32 v162, v162, v166
	v_add_f32_e32 v163, v163, v167
	ds_write_b128 v21, v[160:163]
	s_waitcnt lgkmcnt(0)
	s_barrier
	s_cmp_lt_u32 s93, 4
	s_cbranch_scc0 .Lp0m_s3skip_b0
	ds_read_b32 v168, v22
	ds_read_b32 v169, v22 offset:1024
	ds_read_b32 v170, v22 offset:2048
	ds_read_b32 v171, v22 offset:3072
	ds_read_b32 v172, v22 offset:4096
	ds_read_b32 v173, v22 offset:5120
	ds_read_b32 v174, v22 offset:6144
	ds_read_b32 v175, v22 offset:7168
	s_waitcnt lgkmcnt(6)
	v_add_f32_e32 v168, v168, v169
	s_waitcnt lgkmcnt(5)
	v_add_f32_e32 v168, v168, v170
	s_waitcnt lgkmcnt(4)
	v_add_f32_e32 v168, v168, v171
	s_waitcnt lgkmcnt(3)
	v_add_f32_e32 v168, v168, v172
	s_waitcnt lgkmcnt(2)
	v_add_f32_e32 v168, v168, v173
	s_waitcnt lgkmcnt(1)
	v_add_f32_e32 v168, v168, v174
	s_waitcnt lgkmcnt(0)
	v_add_f32_e32 v168, v168, v175
	global_store_dword v23, v168, s[52:53]
.Lp0m_s3skip_b0:
	v_add_u32_e32 v23, 0x40000, v23
	s_add_u32 s44, s44, 0x1000000
	s_addc_u32 s45, s45, 0
	global_load_dwordx4 v[32:35], v28, s[44:45] nt
	global_load_dwordx4 v[36:39], v28, s[44:45] offset:1024 nt
	global_load_dwordx4 v[40:43], v28, s[44:45] offset:2048 nt
	global_load_dwordx4 v[44:47], v28, s[44:45] offset:3072 nt
	s_add_u32 s10, s44, 0x800000
	s_addc_u32 s11, s45, 0
	global_load_dwordx4 v[48:51], v28, s[10:11] nt
	global_load_dwordx4 v[52:55], v28, s[10:11] offset:1024 nt
	global_load_dwordx4 v[56:59], v28, s[10:11] offset:2048 nt
	global_load_dwordx4 v[60:63], v28, s[10:11] offset:3072 nt
	s_waitcnt vmcnt(16)
	v_mul_f32_e32 v64, v192, v192
	v_fmac_f32_e32 v64, v193, v193
	v_mul_f32_e32 v65, v194, v194
	v_fmac_f32_e32 v65, v195, v195
	v_add_f32_e32 v64, v64, v65
	v_mul_f32_e32 v66, v196, v196
	v_fmac_f32_e32 v66, v197, v197
	v_mul_f32_e32 v67, v198, v198
	v_fmac_f32_e32 v67, v199, v199
	v_add_f32_e32 v66, v66, v67
	v_mul_f32_e32 v68, v200, v200
	v_fmac_f32_e32 v68, v201, v201
	v_mul_f32_e32 v69, v202, v202
	v_fmac_f32_e32 v69, v203, v203
	v_add_f32_e32 v68, v68, v69
	v_mul_f32_e32 v70, v204, v204
	v_fmac_f32_e32 v70, v205, v205
	v_mul_f32_e32 v71, v206, v206
	v_fmac_f32_e32 v71, v207, v207
	v_add_f32_e32 v70, v70, v71
	v_add_f32_e32 v64, v64, v66
	v_add_f32_e32 v64, v64, v68
	v_add_f32_e32 v64, v64, v70
	s_nop 1
	v_add_f32_dpp v88, v64, v64 quad_perm:[1,0,3,2] row_mask:0xf bank_mask:0xf
	s_nop 1
	v_add_f32_dpp v88, v88, v88 quad_perm:[2,3,0,1] row_mask:0xf bank_mask:0xf
	s_nop 1
	v_add_f32_dpp v88, v88, v88 row_half_mirror row_mask:0xf bank_mask:0xf
	s_nop 1
	v_add_f32_dpp v88, v88, v88 row_mirror row_mask:0xf bank_mask:0xf
	s_nop 1
	v_readlane_b32 s48, v88, 0
	v_readlane_b32 s49, v88, 16
	v_readlane_b32 s50, v88, 32
	v_readlane_b32 s51, v88, 48
	s_nop 1
	v_mov_b32_e32 v88, s48
	v_add_f32_e32 v88, s49, v88
	v_add_f32_e32 v88, s50, v88
	v_add_f32_e32 v88, s51, v88
	v_fmamk_f32 v88, v88, 0x3a800000, v16
	v_mul_f32_e32 v89, 0x4b800000, v88
	v_cmp_gt_f32_e64 s[8:9], s3, v88
	s_nop 1
	v_cndmask_b32_e64 v88, v88, v89, s[8:9]
	v_rsq_f32_e32 v88, v88
	s_nop 0
	v_mul_f32_e32 v89, 0x45800000, v88
	v_cndmask_b32_e64 v88, v88, v89, s[8:9]
	v_mul_f32_e32 v192, v192, v88
	v_mul_f32_e32 v193, v193, v88
	v_mul_f32_e32 v194, v194, v88
	v_mul_f32_e32 v195, v195, v88
	v_mul_f32_e32 v196, v196, v88
; #define LAS __attribute__((address_space(3)))
; __device__ __forceinline__ float wave_sum(float v) { for (int o = 32; o >= 1; o >>= 1) v += __shfl_xor(v, o); return v; }
; __device__ __forceinline__ u32x2 pk4(f32x4 v) { u32x2 w; w.x = cvt_pk_bf16(v[0], v[1]); w.y = cvt_pk_bf16(v[2], v[3]); return w; }
; __device__ __forceinline__ void p0_rows(const Args& a, LAS unsigned char* lds, int gw, int NGW, int wave, int lane, int tid) {
;     ...
;         for (int j = 0; j < 4; ++j) { v[j] = xr[64 * j]; s += (v[j][0] * v[j][0] + v[j][1] * v[j][1]) + (v[j][2] * v[j][2] + v[j][3] * v[j][3]); }
;         const float rstd = rsqrtf(wave_sum(s) * (1.f / DM) + EPS);
;         u32x2* ho = (u32x2*)(H + (size_t)row * DM) + lane;
; #pragma unroll
;         for (int j = 0; j < 4; ++j) { v[j] = v[j] * rstd * g[j]; ho[64 * j] = pk4(v[j]); *(LAS f32x4*)(hrow + j * 264 + 4 * lane) = v[j]; }
	v_mul_f32_e32 v197, v197, v88
	v_mul_f32_e32 v198, v198, v88
	v_mul_f32_e32 v199, v199, v88
	v_mul_f32_e32 v200, v200, v88
	v_mul_f32_e32 v201, v201, v88
	v_mul_f32_e32 v202, v202, v88
	v_mul_f32_e32 v203, v203, v88
	v_mul_f32_e32 v204, v204, v88
	v_mul_f32_e32 v205, v205, v88
	v_mul_f32_e32 v206, v206, v88
	v_mul_f32_e32 v207, v207, v88
	v_mul_f32_e32 v192, v0, v192
	v_mul_f32_e32 v193, v1, v193
	v_mul_f32_e32 v194, v2, v194
	v_mul_f32_e32 v195, v3, v195
	v_mul_f32_e32 v196, v4, v196
	v_mul_f32_e32 v197, v5, v197
	v_mul_f32_e32 v198, v6, v198
	v_mul_f32_e32 v199, v7, v199
	v_mul_f32_e32 v200, v8, v200
	v_mul_f32_e32 v201, v9, v201
	v_mul_f32_e32 v202, v10, v202
	v_mul_f32_e32 v203, v11, v203
	v_mul_f32_e32 v204, v12, v204
	v_mul_f32_e32 v205, v13, v205
	v_mul_f32_e32 v206, v14, v206
	v_mul_f32_e32 v207, v15, v207
	s_add_i32 s7, s42, 65792
	v_add_u32_e32 v18, s7, v17
	ds_write_b128 v18, v[192:195]
	ds_write_b128 v18, v[196:199] offset:1024
	ds_write_b128 v18, v[200:203] offset:2048
	ds_write_b128 v18, v[204:207] offset:3072
	v_cvt_pk_bf16_f32 v80, v192, v193
	v_cvt_pk_bf16_f32 v81, v194, v195
	v_cvt_pk_bf16_f32 v82, v196, v197
	v_cvt_pk_bf16_f32 v83, v198, v199
	v_cvt_pk_bf16_f32 v84, v200, v201
	v_cvt_pk_bf16_f32 v85, v202, v203
	v_cvt_pk_bf16_f32 v86, v204, v205
	v_cvt_pk_bf16_f32 v87, v206, v207
	global_store_dwordx2 v29, v[80:81], s[40:41]
	global_store_dwordx2 v29, v[82:83], s[40:41] offset:512
	global_store_dwordx2 v29, v[84:85], s[40:41] offset:1024
	global_store_dwordx2 v29, v[86:87], s[40:41] offset:1536
	v_mul_f32_e32 v64, v208, v208
	v_fmac_f32_e32 v64, v209, v209
	v_mul_f32_e32 v65, v210, v210
	v_fmac_f32_e32 v65, v211, v211
	v_add_f32_e32 v64, v64, v65
	v_mul_f32_e32 v66, v212, v212
	v_fmac_f32_e32 v66, v213, v213
	v_mul_f32_e32 v67, v214, v214
	v_fmac_f32_e32 v67, v215, v215
	v_add_f32_e32 v66, v66, v67
	v_mul_f32_e32 v68, v216, v216
	v_fmac_f32_e32 v68, v217, v217
	v_mul_f32_e32 v69, v218, v218
	v_fmac_f32_e32 v69, v219, v219
	v_add_f32_e32 v68, v68, v69
	v_mul_f32_e32 v70, v220, v220
	v_fmac_f32_e32 v70, v221, v221
	v_mul_f32_e32 v71, v222, v222
	v_fmac_f32_e32 v71, v223, v223
	v_add_f32_e32 v70, v70, v71
	v_add_f32_e32 v64, v64, v66
	v_add_f32_e32 v64, v64, v68
	v_add_f32_e32 v64, v64, v70
	s_nop 1
	v_add_f32_dpp v88, v64, v64 quad_perm:[1,0,3,2] row_mask:0xf bank_mask:0xf
	s_nop 1
	v_add_f32_dpp v88, v88, v88 quad_perm:[2,3,0,1] row_mask:0xf bank_mask:0xf
	s_nop 1
	v_add_f32_dpp v88, v88, v88 row_half_mirror row_mask:0xf bank_mask:0xf
	s_nop 1
	v_add_f32_dpp v88, v88, v88 row_mirror row_mask:0xf bank_mask:0xf
	s_nop 1
	v_readlane_b32 s48, v88, 0
	v_readlane_b32 s49, v88, 16
	v_readlane_b32 s50, v88, 32
	v_readlane_b32 s51, v88, 48
	s_nop 1
	v_mov_b32_e32 v88, s48
	v_add_f32_e32 v88, s49, v88
	v_add_f32_e32 v88, s50, v88
	v_add_f32_e32 v88, s51, v88
	v_fmamk_f32 v88, v88, 0x3a800000, v16
	v_mul_f32_e32 v89, 0x4b800000, v88
	v_cmp_gt_f32_e64 s[8:9], s3, v88
	s_nop 1
	v_cndmask_b32_e64 v88, v88, v89, s[8:9]
	v_rsq_f32_e32 v88, v88
	s_nop 0
	v_mul_f32_e32 v89, 0x45800000, v88
	v_cndmask_b32_e64 v88, v88, v89, s[8:9]
	v_mul_f32_e32 v208, v208, v88
	v_mul_f32_e32 v209, v209, v88
	v_mul_f32_e32 v210, v210, v88
	v_mul_f32_e32 v211, v211, v88
	v_mul_f32_e32 v212, v212, v88
	v_mul_f32_e32 v213, v213, v88
	v_mul_f32_e32 v214, v214, v88
	v_mul_f32_e32 v215, v215, v88
	v_mul_f32_e32 v216, v216, v88
	v_mul_f32_e32 v217, v217, v88
	v_mul_f32_e32 v218, v218, v88
	v_mul_f32_e32 v219, v219, v88
	v_mul_f32_e32 v220, v220, v88
	v_mul_f32_e32 v221, v221, v88
	v_mul_f32_e32 v222, v222, v88
	v_mul_f32_e32 v223, v223, v88
	v_mul_f32_e32 v208, v0, v208
	v_mul_f32_e32 v209, v1, v209
	v_mul_f32_e32 v210, v2, v210
	v_mul_f32_e32 v211, v3, v211
	v_mul_f32_e32 v212, v4, v212
	v_mul_f32_e32 v213, v5, v213
	v_mul_f32_e32 v214, v6, v214
	v_mul_f32_e32 v215, v7, v215
	v_mul_f32_e32 v216, v8, v216
	v_mul_f32_e32 v217, v9, v217
	v_mul_f32_e32 v218, v10, v218
	v_mul_f32_e32 v219, v11, v219
	v_mul_f32_e32 v220, v12, v220
	v_mul_f32_e32 v221, v13, v221
	v_mul_f32_e32 v222, v14, v222
	v_mul_f32_e32 v223, v15, v223
	s_add_i32 s7, s42, 98688
	v_add_u32_e32 v18, s7, v17
	ds_write_b128 v18, v[208:211]
	ds_write_b128 v18, v[212:215] offset:1024
	ds_write_b128 v18, v[216:219] offset:2048
	ds_write_b128 v18, v[220:223] offset:3072
	s_add_u32 s10, s40, 0x400000
	s_addc_u32 s11, s41, 0
	v_cvt_pk_bf16_f32 v80, v208, v209
	v_cvt_pk_bf16_f32 v81, v210, v211
	v_cvt_pk_bf16_f32 v82, v212, v213
	v_cvt_pk_bf16_f32 v83, v214, v215
	v_cvt_pk_bf16_f32 v84, v216, v217
	v_cvt_pk_bf16_f32 v85, v218, v219
	v_cvt_pk_bf16_f32 v86, v220, v221
	v_cvt_pk_bf16_f32 v87, v222, v223
	global_store_dwordx2 v29, v[80:81], s[10:11]
	global_store_dwordx2 v29, v[82:83], s[10:11] offset:512
	global_store_dwordx2 v29, v[84:85], s[10:11] offset:1024
	global_store_dwordx2 v29, v[86:87], s[10:11] offset:1536
	s_add_u32 s40, s40, 0x800000
	s_addc_u32 s41, s41, 0
	s_waitcnt lgkmcnt(0)
	s_barrier
; #define LAS __attribute__((address_space(3)))
; __device__ __forceinline__ void p0_rows(const Args& a, LAS unsigned char* lds, int gw, int NGW, int wave, int lane, int tid) {
;     ...
;         const f32x4* xr = (const f32x4*)xrow_ptr(a, row) + lane; f32x4 v[4]; float s = 0.f;
; #pragma unroll
;         for (int j = 0; j < 4; ++j) { v[j] = xr[64 * j]; s += (v[j][0] * v[j][0] + v[j][1] * v[j][1]) + (v[j][2] * v[j][2] + v[j][3] * v[j][3]); }
;     ...
;         const int jj = lane & 15, p = lane >> 4; float acc = 0.f;
;         const LAS float* hp = hrow + p * 264; const LAS float* wp = WdL + p * 4112 + jj;
; #pragma unroll 8
;         for (int kk = 0; kk < 256; ++kk) acc += hp[kk] * wp[kk * 16];
;         acc += __shfl_xor(acc, 16); acc += __shfl_xor(acc, 32);
;         if (lane < 16) DLR[(size_t)row * 16 + jj] = acc;
	ds_read_b128 v[128:131], v20
	ds_read_b128 v[132:135], v20 offset:16
	ds_read_b128 v[136:139], v20 offset:32
	ds_read_b128 v[140:143], v20 offset:48
	ds_read_b128 v[144:147], v20 offset:64
	ds_read_b128 v[148:151], v20 offset:80
	ds_read_b128 v[152:155], v20 offset:96
	ds_read_b128 v[156:159], v20 offset:112
	s_waitcnt lgkmcnt(7)
	v_mfma_f32_16x16x4_f32 v[160:163], v128, v96, 0
	v_mfma_f32_16x16x4_f32 v[164:167], v129, v97, 0
	v_mfma_f32_16x16x4_f32 v[160:163], v130, v98, v[160:163]
	v_mfma_f32_16x16x4_f32 v[164:167], v131, v99, v[164:167]
	s_waitcnt lgkmcnt(6)
	v_mfma_f32_16x16x4_f32 v[160:163], v132, v100, v[160:163]
	v_mfma_f32_16x16x4_f32 v[164:167], v133, v101, v[164:167]
	v_mfma_f32_16x16x4_f32 v[160:163], v134, v102, v[160:163]
	v_mfma_f32_16x16x4_f32 v[164:167], v135, v103, v[164:167]
	s_waitcnt lgkmcnt(5)
	v_mfma_f32_16x16x4_f32 v[160:163], v136, v104, v[160:163]
	v_mfma_f32_16x16x4_f32 v[164:167], v137, v105, v[164:167]
	v_mfma_f32_16x16x4_f32 v[160:163], v138, v106, v[160:163]
	v_mfma_f32_16x16x4_f32 v[164:167], v139, v107, v[164:167]
	s_waitcnt lgkmcnt(4)
	v_mfma_f32_16x16x4_f32 v[160:163], v140, v108, v[160:163]
	v_mfma_f32_16x16x4_f32 v[164:167], v141, v109, v[164:167]
	v_mfma_f32_16x16x4_f32 v[160:163], v142, v110, v[160:163]
	v_mfma_f32_16x16x4_f32 v[164:167], v143, v111, v[164:167]
	s_waitcnt lgkmcnt(3)
	v_mfma_f32_16x16x4_f32 v[160:163], v144, v112, v[160:163]
	v_mfma_f32_16x16x4_f32 v[164:167], v145, v113, v[164:167]
	v_mfma_f32_16x16x4_f32 v[160:163], v146, v114, v[160:163]
	v_mfma_f32_16x16x4_f32 v[164:167], v147, v115, v[164:167]
	s_waitcnt lgkmcnt(2)
	v_mfma_f32_16x16x4_f32 v[160:163], v148, v116, v[160:163]
	v_mfma_f32_16x16x4_f32 v[164:167], v149, v117, v[164:167]
	v_mfma_f32_16x16x4_f32 v[160:163], v150, v118, v[160:163]
	v_mfma_f32_16x16x4_f32 v[164:167], v151, v119, v[164:167]
	s_waitcnt lgkmcnt(1)
	v_mfma_f32_16x16x4_f32 v[160:163], v152, v120, v[160:163]
	v_mfma_f32_16x16x4_f32 v[164:167], v153, v121, v[164:167]
	v_mfma_f32_16x16x4_f32 v[160:163], v154, v122, v[160:163]
	v_mfma_f32_16x16x4_f32 v[164:167], v155, v123, v[164:167]
	s_waitcnt lgkmcnt(0)
	v_mfma_f32_16x16x4_f32 v[160:163], v156, v124, v[160:163]
	v_mfma_f32_16x16x4_f32 v[164:167], v157, v125, v[164:167]
	v_mfma_f32_16x16x4_f32 v[160:163], v158, v126, v[160:163]
	v_mfma_f32_16x16x4_f32 v[164:167], v159, v127, v[164:167]
	s_nop 9
	v_add_f32_e32 v160, v160, v164
	v_add_f32_e32 v161, v161, v165
	v_add_f32_e32 v162, v162, v166
	v_add_f32_e32 v163, v163, v167
	ds_write_b128 v21, v[160:163]
	s_waitcnt lgkmcnt(0)
	s_barrier
	s_cmp_lt_u32 s93, 4
	s_cbranch_scc0 .Lp0m_s3skip_b1
	ds_read_b32 v168, v22
	ds_read_b32 v169, v22 offset:1024
	ds_read_b32 v170, v22 offset:2048
	ds_read_b32 v171, v22 offset:3072
	ds_read_b32 v172, v22 offset:4096
	ds_read_b32 v173, v22 offset:5120
	ds_read_b32 v174, v22 offset:6144
	ds_read_b32 v175, v22 offset:7168
	s_waitcnt lgkmcnt(6)
	v_add_f32_e32 v168, v168, v169
	s_waitcnt lgkmcnt(5)
	v_add_f32_e32 v168, v168, v170
	s_waitcnt lgkmcnt(4)
	v_add_f32_e32 v168, v168, v171
	s_waitcnt lgkmcnt(3)
	v_add_f32_e32 v168, v168, v172
	s_waitcnt lgkmcnt(2)
	v_add_f32_e32 v168, v168, v173
	s_waitcnt lgkmcnt(1)
	v_add_f32_e32 v168, v168, v174
	s_waitcnt lgkmcnt(0)
	v_add_f32_e32 v168, v168, v175
	global_store_dword v23, v168, s[52:53]
.Lp0m_s3skip_b1:
	v_add_u32_e32 v23, 0x40000, v23
	s_add_u32 s44, s44, 0x1000000
	s_addc_u32 s45, s45, 0
	global_load_dwordx4 v[192:195], v28, s[44:45] nt
	global_load_dwordx4 v[196:199], v28, s[44:45] offset:1024 nt
	global_load_dwordx4 v[200:203], v28, s[44:45] offset:2048 nt
	global_load_dwordx4 v[204:207], v28, s[44:45] offset:3072 nt
	s_add_u32 s10, s44, 0x800000
	s_addc_u32 s11, s45, 0
	global_load_dwordx4 v[208:211], v28, s[10:11] nt
	global_load_dwordx4 v[212:215], v28, s[10:11] offset:1024 nt
	global_load_dwordx4 v[216:219], v28, s[10:11] offset:2048 nt
	global_load_dwordx4 v[220:223], v28, s[10:11] offset:3072 nt
	s_waitcnt vmcnt(16)
	v_mul_f32_e32 v64, v32, v32
	v_fmac_f32_e32 v64, v33, v33
	v_mul_f32_e32 v65, v34, v34
	v_fmac_f32_e32 v65, v35, v35
	v_add_f32_e32 v64, v64, v65
	v_mul_f32_e32 v66, v36, v36
	v_fmac_f32_e32 v66, v37, v37
	v_mul_f32_e32 v67, v38, v38
	v_fmac_f32_e32 v67, v39, v39
	v_add_f32_e32 v66, v66, v67
	v_mul_f32_e32 v68, v40, v40
	v_fmac_f32_e32 v68, v41, v41
	v_mul_f32_e32 v69, v42, v42
	v_fmac_f32_e32 v69, v43, v43
	v_add_f32_e32 v68, v68, v69
	v_mul_f32_e32 v70, v44, v44
	v_fmac_f32_e32 v70, v45, v45
	v_mul_f32_e32 v71, v46, v46
	v_fmac_f32_e32 v71, v47, v47
	v_add_f32_e32 v70, v70, v71
	v_add_f32_e32 v64, v64, v66
	v_add_f32_e32 v64, v64, v68
	v_add_f32_e32 v64, v64, v70
	s_nop 1
	v_add_f32_dpp v88, v64, v64 quad_perm:[1,0,3,2] row_mask:0xf bank_mask:0xf
	s_nop 1
	v_add_f32_dpp v88, v88, v88 quad_perm:[2,3,0,1] row_mask:0xf bank_mask:0xf
	s_nop 1
	v_add_f32_dpp v88, v88, v88 row_half_mirror row_mask:0xf bank_mask:0xf
	s_nop 1
	v_add_f32_dpp v88, v88, v88 row_mirror row_mask:0xf bank_mask:0xf
	s_nop 1
	v_readlane_b32 s48, v88, 0
	v_readlane_b32 s49, v88, 16
	v_readlane_b32 s50, v88, 32
	v_readlane_b32 s51, v88, 48
	s_nop 1
	v_mov_b32_e32 v88, s48
	v_add_f32_e32 v88, s49, v88
	v_add_f32_e32 v88, s50, v88
	v_add_f32_e32 v88, s51, v88
	v_fmamk_f32 v88, v88, 0x3a800000, v16
	v_mul_f32_e32 v89, 0x4b800000, v88
	v_cmp_gt_f32_e64 s[8:9], s3, v88
	s_nop 1
	v_cndmask_b32_e64 v88, v88, v89, s[8:9]
	v_rsq_f32_e32 v88, v88
	s_nop 0
	v_mul_f32_e32 v89, 0x45800000, v88
	v_cndmask_b32_e64 v88, v88, v89, s[8:9]
	v_mul_f32_e32 v32, v32, v88
	v_mul_f32_e32 v33, v33, v88
	v_mul_f32_e32 v34, v34, v88
	v_mul_f32_e32 v35, v35, v88
	v_mul_f32_e32 v36, v36, v88
	v_mul_f32_e32 v37, v37, v88
; #define LAS __attribute__((address_space(3)))
; __device__ __forceinline__ float wave_sum(float v) { for (int o = 32; o >= 1; o >>= 1) v += __shfl_xor(v, o); return v; }
; __device__ __forceinline__ u32x2 pk4(f32x4 v) { u32x2 w; w.x = cvt_pk_bf16(v[0], v[1]); w.y = cvt_pk_bf16(v[2], v[3]); return w; }
; __device__ __forceinline__ void p0_rows(const Args& a, LAS unsigned char* lds, int gw, int NGW, int wave, int lane, int tid) {
;     ...
;         for (int j = 0; j < 4; ++j) { v[j] = xr[64 * j]; s += (v[j][0] * v[j][0] + v[j][1] * v[j][1]) + (v[j][2] * v[j][2] + v[j][3] * v[j][3]); }
;         const float rstd = rsqrtf(wave_sum(s) * (1.f / DM) + EPS);
;         u32x2* ho = (u32x2*)(H + (size_t)row * DM) + lane;
; #pragma unroll
;         for (int j = 0; j < 4; ++j) { v[j] = v[j] * rstd * g[j]; ho[64 * j] = pk4(v[j]); *(LAS f32x4*)(hrow + j * 264 + 4 * lane) = v[j]; }
	v_mul_f32_e32 v38, v38, v88
	v_mul_f32_e32 v39, v39, v88
	v_mul_f32_e32 v40, v40, v88
	v_mul_f32_e32 v41, v41, v88
	v_mul_f32_e32 v42, v42, v88
	v_mul_f32_e32 v43, v43, v88
	v_mul_f32_e32 v44, v44, v88
	v_mul_f32_e32 v45, v45, v88
	v_mul_f32_e32 v46, v46, v88
	v_mul_f32_e32 v47, v47, v88
	v_mul_f32_e32 v32, v0, v32
	v_mul_f32_e32 v33, v1, v33
	v_mul_f32_e32 v34, v2, v34
	v_mul_f32_e32 v35, v3, v35
	v_mul_f32_e32 v36, v4, v36
	v_mul_f32_e32 v37, v5, v37
	v_mul_f32_e32 v38, v6, v38
	v_mul_f32_e32 v39, v7, v39
	v_mul_f32_e32 v40, v8, v40
	v_mul_f32_e32 v41, v9, v41
	v_mul_f32_e32 v42, v10, v42
	v_mul_f32_e32 v43, v11, v43
	v_mul_f32_e32 v44, v12, v44
	v_mul_f32_e32 v45, v13, v45
	v_mul_f32_e32 v46, v14, v46
	v_mul_f32_e32 v47, v15, v47
	s_add_i32 s7, s42, 0
	v_add_u32_e32 v18, s7, v17
	ds_write_b128 v18, v[32:35]
	ds_write_b128 v18, v[36:39] offset:1024
	ds_write_b128 v18, v[40:43] offset:2048
	ds_write_b128 v18, v[44:47] offset:3072
	v_cvt_pk_bf16_f32 v80, v32, v33
	v_cvt_pk_bf16_f32 v81, v34, v35
	v_cvt_pk_bf16_f32 v82, v36, v37
	v_cvt_pk_bf16_f32 v83, v38, v39
	v_cvt_pk_bf16_f32 v84, v40, v41
	v_cvt_pk_bf16_f32 v85, v42, v43
	v_cvt_pk_bf16_f32 v86, v44, v45
	v_cvt_pk_bf16_f32 v87, v46, v47
	global_store_dwordx2 v29, v[80:81], s[40:41]
	global_store_dwordx2 v29, v[82:83], s[40:41] offset:512
	global_store_dwordx2 v29, v[84:85], s[40:41] offset:1024
	global_store_dwordx2 v29, v[86:87], s[40:41] offset:1536
	v_mul_f32_e32 v64, v48, v48
	v_fmac_f32_e32 v64, v49, v49
	v_mul_f32_e32 v65, v50, v50
	v_fmac_f32_e32 v65, v51, v51
	v_add_f32_e32 v64, v64, v65
	v_mul_f32_e32 v66, v52, v52
	v_fmac_f32_e32 v66, v53, v53
	v_mul_f32_e32 v67, v54, v54
	v_fmac_f32_e32 v67, v55, v55
	v_add_f32_e32 v66, v66, v67
	v_mul_f32_e32 v68, v56, v56
	v_fmac_f32_e32 v68, v57, v57
	v_mul_f32_e32 v69, v58, v58
	v_fmac_f32_e32 v69, v59, v59
	v_add_f32_e32 v68, v68, v69
	v_mul_f32_e32 v70, v60, v60
	v_fmac_f32_e32 v70, v61, v61
	v_mul_f32_e32 v71, v62, v62
	v_fmac_f32_e32 v71, v63, v63
	v_add_f32_e32 v70, v70, v71
	v_add_f32_e32 v64, v64, v66
	v_add_f32_e32 v64, v64, v68
	v_add_f32_e32 v64, v64, v70
	s_nop 1
	v_add_f32_dpp v88, v64, v64 quad_perm:[1,0,3,2] row_mask:0xf bank_mask:0xf
	s_nop 1
	v_add_f32_dpp v88, v88, v88 quad_perm:[2,3,0,1] row_mask:0xf bank_mask:0xf
	s_nop 1
	v_add_f32_dpp v88, v88, v88 row_half_mirror row_mask:0xf bank_mask:0xf
	s_nop 1
	v_add_f32_dpp v88, v88, v88 row_mirror row_mask:0xf bank_mask:0xf
	s_nop 1
	v_readlane_b32 s48, v88, 0
	v_readlane_b32 s49, v88, 16
	v_readlane_b32 s50, v88, 32
	v_readlane_b32 s51, v88, 48
	s_nop 1
	v_mov_b32_e32 v88, s48
	v_add_f32_e32 v88, s49, v88
	v_add_f32_e32 v88, s50, v88
	v_add_f32_e32 v88, s51, v88
	v_fmamk_f32 v88, v88, 0x3a800000, v16
	v_mul_f32_e32 v89, 0x4b800000, v88
	v_cmp_gt_f32_e64 s[8:9], s3, v88
	s_nop 1
	v_cndmask_b32_e64 v88, v88, v89, s[8:9]
	v_rsq_f32_e32 v88, v88
	s_nop 0
	v_mul_f32_e32 v89, 0x45800000, v88
	v_cndmask_b32_e64 v88, v88, v89, s[8:9]
	v_mul_f32_e32 v48, v48, v88
	v_mul_f32_e32 v49, v49, v88
	v_mul_f32_e32 v50, v50, v88
	v_mul_f32_e32 v51, v51, v88
	v_mul_f32_e32 v52, v52, v88
	v_mul_f32_e32 v53, v53, v88
	v_mul_f32_e32 v54, v54, v88
	v_mul_f32_e32 v55, v55, v88
	v_mul_f32_e32 v56, v56, v88
	v_mul_f32_e32 v57, v57, v88
	v_mul_f32_e32 v58, v58, v88
	v_mul_f32_e32 v59, v59, v88
	v_mul_f32_e32 v60, v60, v88
	v_mul_f32_e32 v61, v61, v88
	v_mul_f32_e32 v62, v62, v88
	v_mul_f32_e32 v63, v63, v88
	v_mul_f32_e32 v48, v0, v48
	v_mul_f32_e32 v49, v1, v49
	v_mul_f32_e32 v50, v2, v50
	v_mul_f32_e32 v51, v3, v51
	v_mul_f32_e32 v52, v4, v52
	v_mul_f32_e32 v53, v5, v53
	v_mul_f32_e32 v54, v6, v54
	v_mul_f32_e32 v55, v7, v55
	v_mul_f32_e32 v56, v8, v56
	v_mul_f32_e32 v57, v9, v57
	v_mul_f32_e32 v58, v10, v58
	v_mul_f32_e32 v59, v11, v59
	v_mul_f32_e32 v60, v12, v60
	v_mul_f32_e32 v61, v13, v61
	v_mul_f32_e32 v62, v14, v62
	v_mul_f32_e32 v63, v15, v63
	s_add_i32 s7, s42, 32896
	v_add_u32_e32 v18, s7, v17
	ds_write_b128 v18, v[48:51]
	ds_write_b128 v18, v[52:55] offset:1024
	ds_write_b128 v18, v[56:59] offset:2048
	ds_write_b128 v18, v[60:63] offset:3072
	s_add_u32 s10, s40, 0x400000
	s_addc_u32 s11, s41, 0
	v_cvt_pk_bf16_f32 v80, v48, v49
	v_cvt_pk_bf16_f32 v81, v50, v51
	v_cvt_pk_bf16_f32 v82, v52, v53
	v_cvt_pk_bf16_f32 v83, v54, v55
	v_cvt_pk_bf16_f32 v84, v56, v57
	v_cvt_pk_bf16_f32 v85, v58, v59
	v_cvt_pk_bf16_f32 v86, v60, v61
	v_cvt_pk_bf16_f32 v87, v62, v63
	global_store_dwordx2 v29, v[80:81], s[10:11]
	global_store_dwordx2 v29, v[82:83], s[10:11] offset:512
	global_store_dwordx2 v29, v[84:85], s[10:11] offset:1024
	global_store_dwordx2 v29, v[86:87], s[10:11] offset:1536
	s_add_u32 s40, s40, 0x800000
	s_addc_u32 s41, s41, 0
	s_waitcnt lgkmcnt(0)
	s_barrier
; #define LAS __attribute__((address_space(3)))
; __device__ __forceinline__ void p0_rows(const Args& a, LAS unsigned char* lds, int gw, int NGW, int wave, int lane, int tid) {
;     ...
;     for (int row = gw; row < MT; row += NGW) {
;         const f32x4* xr = (const f32x4*)xrow_ptr(a, row) + lane; f32x4 v[4]; float s = 0.f;
; #pragma unroll
;         for (int j = 0; j < 4; ++j) { v[j] = xr[64 * j]; s += (v[j][0] * v[j][0] + v[j][1] * v[j][1]) + (v[j][2] * v[j][2] + v[j][3] * v[j][3]); }
;     ...
;         const int jj = lane & 15, p = lane >> 4; float acc = 0.f;
;         const LAS float* hp = hrow + p * 264; const LAS float* wp = WdL + p * 4112 + jj;
; #pragma unroll 8
;         for (int kk = 0; kk < 256; ++kk) acc += hp[kk] * wp[kk * 16];
;         acc += __shfl_xor(acc, 16); acc += __shfl_xor(acc, 32);
;         if (lane < 16) DLR[(size_t)row * 16 + jj] = acc;
	ds_read_b128 v[128:131], v19
	ds_read_b128 v[132:135], v19 offset:16
	ds_read_b128 v[136:139], v19 offset:32
	ds_read_b128 v[140:143], v19 offset:48
	ds_read_b128 v[144:147], v19 offset:64
	ds_read_b128 v[148:151], v19 offset:80
	ds_read_b128 v[152:155], v19 offset:96
	ds_read_b128 v[156:159], v19 offset:112
	s_waitcnt lgkmcnt(7)
	v_mfma_f32_16x16x4_f32 v[160:163], v128, v96, 0
	v_mfma_f32_16x16x4_f32 v[164:167], v129, v97, 0
	v_mfma_f32_16x16x4_f32 v[160:163], v130, v98, v[160:163]
	v_mfma_f32_16x16x4_f32 v[164:167], v131, v99, v[164:167]
	s_waitcnt lgkmcnt(6)
	v_mfma_f32_16x16x4_f32 v[160:163], v132, v100, v[160:163]
	v_mfma_f32_16x16x4_f32 v[164:167], v133, v101, v[164:167]
	v_mfma_f32_16x16x4_f32 v[160:163], v134, v102, v[160:163]
	v_mfma_f32_16x16x4_f32 v[164:167], v135, v103, v[164:167]
	s_waitcnt lgkmcnt(5)
	v_mfma_f32_16x16x4_f32 v[160:163], v136, v104, v[160:163]
	v_mfma_f32_16x16x4_f32 v[164:167], v137, v105, v[164:167]
	v_mfma_f32_16x16x4_f32 v[160:163], v138, v106, v[160:163]
	v_mfma_f32_16x16x4_f32 v[164:167], v139, v107, v[164:167]
	s_waitcnt lgkmcnt(4)
	v_mfma_f32_16x16x4_f32 v[160:163], v140, v108, v[160:163]
	v_mfma_f32_16x16x4_f32 v[164:167], v141, v109, v[164:167]
	v_mfma_f32_16x16x4_f32 v[160:163], v142, v110, v[160:163]
	v_mfma_f32_16x16x4_f32 v[164:167], v143, v111, v[164:167]
	s_waitcnt lgkmcnt(3)
	v_mfma_f32_16x16x4_f32 v[160:163], v144, v112, v[160:163]
	v_mfma_f32_16x16x4_f32 v[164:167], v145, v113, v[164:167]
	v_mfma_f32_16x16x4_f32 v[160:163], v146, v114, v[160:163]
	v_mfma_f32_16x16x4_f32 v[164:167], v147, v115, v[164:167]
	s_waitcnt lgkmcnt(2)
	v_mfma_f32_16x16x4_f32 v[160:163], v148, v116, v[160:163]
	v_mfma_f32_16x16x4_f32 v[164:167], v149, v117, v[164:167]
	v_mfma_f32_16x16x4_f32 v[160:163], v150, v118, v[160:163]
	v_mfma_f32_16x16x4_f32 v[164:167], v151, v119, v[164:167]
	s_waitcnt lgkmcnt(1)
	v_mfma_f32_16x16x4_f32 v[160:163], v152, v120, v[160:163]
	v_mfma_f32_16x16x4_f32 v[164:167], v153, v121, v[164:167]
	v_mfma_f32_16x16x4_f32 v[160:163], v154, v122, v[160:163]
	v_mfma_f32_16x16x4_f32 v[164:167], v155, v123, v[164:167]
	s_waitcnt lgkmcnt(0)
	v_mfma_f32_16x16x4_f32 v[160:163], v156, v124, v[160:163]
	v_mfma_f32_16x16x4_f32 v[164:167], v157, v125, v[164:167]
	v_mfma_f32_16x16x4_f32 v[160:163], v158, v126, v[160:163]
	v_mfma_f32_16x16x4_f32 v[164:167], v159, v127, v[164:167]
	s_nop 9
	v_add_f32_e32 v160, v160, v164
	v_add_f32_e32 v161, v161, v165
	v_add_f32_e32 v162, v162, v166
	v_add_f32_e32 v163, v163, v167
	ds_write_b128 v21, v[160:163]
	s_waitcnt lgkmcnt(0)
	s_barrier
	s_cmp_lt_u32 s93, 4
	s_cbranch_scc0 .Lp0m_s3skip_b2
	ds_read_b32 v168, v22
	ds_read_b32 v169, v22 offset:1024
	ds_read_b32 v170, v22 offset:2048
	ds_read_b32 v171, v22 offset:3072
	ds_read_b32 v172, v22 offset:4096
	ds_read_b32 v173, v22 offset:5120
	ds_read_b32 v174, v22 offset:6144
	ds_read_b32 v175, v22 offset:7168
	s_waitcnt lgkmcnt(6)
	v_add_f32_e32 v168, v168, v169
	s_waitcnt lgkmcnt(5)
	v_add_f32_e32 v168, v168, v170
	s_waitcnt lgkmcnt(4)
	v_add_f32_e32 v168, v168, v171
	s_waitcnt lgkmcnt(3)
	v_add_f32_e32 v168, v168, v172
	s_waitcnt lgkmcnt(2)
	v_add_f32_e32 v168, v168, v173
	s_waitcnt lgkmcnt(1)
	v_add_f32_e32 v168, v168, v174
	s_waitcnt lgkmcnt(0)
	v_add_f32_e32 v168, v168, v175
	global_store_dword v23, v168, s[52:53]
.Lp0m_s3skip_b2:
	v_add_u32_e32 v23, 0x40000, v23
	s_cmpk_lt_i32 s2, 0x80
	s_cbranch_scc0 .Lp0m_tailB
	s_lshl_b32 s10, s81, 12
	s_add_u32 s44, s38, s10
	s_addc_u32 s45, s39, 0
	global_load_dwordx4 v[32:35], v28, s[44:45] nt
	global_load_dwordx4 v[36:39], v28, s[44:45] offset:1024 nt
	global_load_dwordx4 v[40:43], v28, s[44:45] offset:2048 nt
	global_load_dwordx4 v[44:47], v28, s[44:45] offset:3072 nt
	s_waitcnt vmcnt(12)
	v_mul_f32_e32 v64, v192, v192
	v_fmac_f32_e32 v64, v193, v193
	v_mul_f32_e32 v65, v194, v194
	v_fmac_f32_e32 v65, v195, v195
	v_add_f32_e32 v64, v64, v65
	v_mul_f32_e32 v66, v196, v196
	v_fmac_f32_e32 v66, v197, v197
	v_mul_f32_e32 v67, v198, v198
	v_fmac_f32_e32 v67, v199, v199
	v_add_f32_e32 v66, v66, v67
	v_mul_f32_e32 v68, v200, v200
	v_fmac_f32_e32 v68, v201, v201
	v_mul_f32_e32 v69, v202, v202
	v_fmac_f32_e32 v69, v203, v203
	v_add_f32_e32 v68, v68, v69
	v_mul_f32_e32 v70, v204, v204
	v_fmac_f32_e32 v70, v205, v205
	v_mul_f32_e32 v71, v206, v206
	v_fmac_f32_e32 v71, v207, v207
	v_add_f32_e32 v70, v70, v71
	v_add_f32_e32 v64, v64, v66
	v_add_f32_e32 v64, v64, v68
	v_add_f32_e32 v64, v64, v70
	s_nop 1
	v_add_f32_dpp v88, v64, v64 quad_perm:[1,0,3,2] row_mask:0xf bank_mask:0xf
	s_nop 1
	v_add_f32_dpp v88, v88, v88 quad_perm:[2,3,0,1] row_mask:0xf bank_mask:0xf
	s_nop 1
	v_add_f32_dpp v88, v88, v88 row_half_mirror row_mask:0xf bank_mask:0xf
	s_nop 1
	v_add_f32_dpp v88, v88, v88 row_mirror row_mask:0xf bank_mask:0xf
	s_nop 1
	v_readlane_b32 s48, v88, 0
	v_readlane_b32 s49, v88, 16
	v_readlane_b32 s50, v88, 32
	v_readlane_b32 s51, v88, 48
	s_nop 1
	v_mov_b32_e32 v88, s48
	v_add_f32_e32 v88, s49, v88
	v_add_f32_e32 v88, s50, v88
	v_add_f32_e32 v88, s51, v88
	v_fmamk_f32 v88, v88, 0x3a800000, v16
	v_mul_f32_e32 v89, 0x4b800000, v88
	v_cmp_gt_f32_e64 s[8:9], s3, v88
	s_nop 1
	v_cndmask_b32_e64 v88, v88, v89, s[8:9]
	v_rsq_f32_e32 v88, v88
	s_nop 0
	v_mul_f32_e32 v89, 0x45800000, v88
	v_cndmask_b32_e64 v88, v88, v89, s[8:9]
	v_mul_f32_e32 v192, v192, v88
	v_mul_f32_e32 v193, v193, v88
	v_mul_f32_e32 v194, v194, v88
	v_mul_f32_e32 v195, v195, v88
	v_mul_f32_e32 v196, v196, v88
	v_mul_f32_e32 v197, v197, v88
	v_mul_f32_e32 v198, v198, v88
	v_mul_f32_e32 v199, v199, v88
	v_mul_f32_e32 v200, v200, v88
	v_mul_f32_e32 v201, v201, v88
	v_mul_f32_e32 v202, v202, v88
	v_mul_f32_e32 v203, v203, v88
; #define LAS __attribute__((address_space(3)))
; __device__ __forceinline__ float wave_sum(float v) { for (int o = 32; o >= 1; o >>= 1) v += __shfl_xor(v, o); return v; }
; __device__ __forceinline__ u32x2 pk4(f32x4 v) { u32x2 w; w.x = cvt_pk_bf16(v[0], v[1]); w.y = cvt_pk_bf16(v[2], v[3]); return w; }
; __device__ __forceinline__ void p0_rows(const Args& a, LAS unsigned char* lds, int gw, int NGW, int wave, int lane, int tid) {
;     ...
;         for (int j = 0; j < 4; ++j) { v[j] = xr[64 * j]; s += (v[j][0] * v[j][0] + v[j][1] * v[j][1]) + (v[j][2] * v[j][2] + v[j][3] * v[j][3]); }
;         const float rstd = rsqrtf(wave_sum(s) * (1.f / DM) + EPS);
;         u32x2* ho = (u32x2*)(H + (size_t)row * DM) + lane;
; #pragma unroll
;         for (int j = 0; j < 4; ++j) { v[j] = v[j] * rstd * g[j]; ho[64 * j] = pk4(v[j]); *(LAS f32x4*)(hrow + j * 264 + 4 * lane) = v[j]; }
	v_mul_f32_e32 v204, v204, v88
	v_mul_f32_e32 v205, v205, v88
	v_mul_f32_e32 v206, v206, v88
	v_mul_f32_e32 v207, v207, v88
	v_mul_f32_e32 v192, v0, v192
	v_mul_f32_e32 v193, v1, v193
	v_mul_f32_e32 v194, v2, v194
	v_mul_f32_e32 v195, v3, v195
	v_mul_f32_e32 v196, v4, v196
	v_mul_f32_e32 v197, v5, v197
	v_mul_f32_e32 v198, v6, v198
	v_mul_f32_e32 v199, v7, v199
	v_mul_f32_e32 v200, v8, v200
	v_mul_f32_e32 v201, v9, v201
	v_mul_f32_e32 v202, v10, v202
	v_mul_f32_e32 v203, v11, v203
	v_mul_f32_e32 v204, v12, v204
	v_mul_f32_e32 v205, v13, v205
	v_mul_f32_e32 v206, v14, v206
	v_mul_f32_e32 v207, v15, v207
	s_add_i32 s7, s42, 65792
	v_add_u32_e32 v18, s7, v17
	ds_write_b128 v18, v[192:195]
	ds_write_b128 v18, v[196:199] offset:1024
	ds_write_b128 v18, v[200:203] offset:2048
	ds_write_b128 v18, v[204:207] offset:3072
	v_cvt_pk_bf16_f32 v80, v192, v193
	v_cvt_pk_bf16_f32 v81, v194, v195
	v_cvt_pk_bf16_f32 v82, v196, v197
	v_cvt_pk_bf16_f32 v83, v198, v199
	v_cvt_pk_bf16_f32 v84, v200, v201
	v_cvt_pk_bf16_f32 v85, v202, v203
	v_cvt_pk_bf16_f32 v86, v204, v205
	v_cvt_pk_bf16_f32 v87, v206, v207
	global_store_dwordx2 v29, v[80:81], s[40:41]
	global_store_dwordx2 v29, v[82:83], s[40:41] offset:512
	global_store_dwordx2 v29, v[84:85], s[40:41] offset:1024
	global_store_dwordx2 v29, v[86:87], s[40:41] offset:1536
	v_mul_f32_e32 v64, v208, v208
	v_fmac_f32_e32 v64, v209, v209
	v_mul_f32_e32 v65, v210, v210
	v_fmac_f32_e32 v65, v211, v211
	v_add_f32_e32 v64, v64, v65
	v_mul_f32_e32 v66, v212, v212
	v_fmac_f32_e32 v66, v213, v213
	v_mul_f32_e32 v67, v214, v214
	v_fmac_f32_e32 v67, v215, v215
	v_add_f32_e32 v66, v66, v67
	v_mul_f32_e32 v68, v216, v216
	v_fmac_f32_e32 v68, v217, v217
	v_mul_f32_e32 v69, v218, v218
	v_fmac_f32_e32 v69, v219, v219
	v_add_f32_e32 v68, v68, v69
	v_mul_f32_e32 v70, v220, v220
	v_fmac_f32_e32 v70, v221, v221
	v_mul_f32_e32 v71, v222, v222
	v_fmac_f32_e32 v71, v223, v223
	v_add_f32_e32 v70, v70, v71
	v_add_f32_e32 v64, v64, v66
	v_add_f32_e32 v64, v64, v68
	v_add_f32_e32 v64, v64, v70
	s_nop 1
	v_add_f32_dpp v88, v64, v64 quad_perm:[1,0,3,2] row_mask:0xf bank_mask:0xf
	s_nop 1
	v_add_f32_dpp v88, v88, v88 quad_perm:[2,3,0,1] row_mask:0xf bank_mask:0xf
	s_nop 1
	v_add_f32_dpp v88, v88, v88 row_half_mirror row_mask:0xf bank_mask:0xf
	s_nop 1
	v_add_f32_dpp v88, v88, v88 row_mirror row_mask:0xf bank_mask:0xf
	s_nop 1
	v_readlane_b32 s48, v88, 0
	v_readlane_b32 s49, v88, 16
	v_readlane_b32 s50, v88, 32
	v_readlane_b32 s51, v88, 48
	s_nop 1
	v_mov_b32_e32 v88, s48
	v_add_f32_e32 v88, s49, v88
	v_add_f32_e32 v88, s50, v88
	v_add_f32_e32 v88, s51, v88
	v_fmamk_f32 v88, v88, 0x3a800000, v16
	v_mul_f32_e32 v89, 0x4b800000, v88
	v_cmp_gt_f32_e64 s[8:9], s3, v88
	s_nop 1
	v_cndmask_b32_e64 v88, v88, v89, s[8:9]
	v_rsq_f32_e32 v88, v88
	s_nop 0
	v_mul_f32_e32 v89, 0x45800000, v88
	v_cndmask_b32_e64 v88, v88, v89, s[8:9]
	v_mul_f32_e32 v208, v208, v88
	v_mul_f32_e32 v209, v209, v88
	v_mul_f32_e32 v210, v210, v88
	v_mul_f32_e32 v211, v211, v88
	v_mul_f32_e32 v212, v212, v88
	v_mul_f32_e32 v213, v213, v88
	v_mul_f32_e32 v214, v214, v88
	v_mul_f32_e32 v215, v215, v88
	v_mul_f32_e32 v216, v216, v88
	v_mul_f32_e32 v217, v217, v88
	v_mul_f32_e32 v218, v218, v88
	v_mul_f32_e32 v219, v219, v88
	v_mul_f32_e32 v220, v220, v88
	v_mul_f32_e32 v221, v221, v88
	v_mul_f32_e32 v222, v222, v88
	v_mul_f32_e32 v223, v223, v88
	v_mul_f32_e32 v208, v0, v208
	v_mul_f32_e32 v209, v1, v209
	v_mul_f32_e32 v210, v2, v210
	v_mul_f32_e32 v211, v3, v211
	v_mul_f32_e32 v212, v4, v212
	v_mul_f32_e32 v213, v5, v213
	v_mul_f32_e32 v214, v6, v214
	v_mul_f32_e32 v215, v7, v215
	v_mul_f32_e32 v216, v8, v216
	v_mul_f32_e32 v217, v9, v217
	v_mul_f32_e32 v218, v10, v218
	v_mul_f32_e32 v219, v11, v219
	v_mul_f32_e32 v220, v12, v220
	v_mul_f32_e32 v221, v13, v221
	v_mul_f32_e32 v222, v14, v222
	v_mul_f32_e32 v223, v15, v223
	s_add_i32 s7, s42, 98688
	v_add_u32_e32 v18, s7, v17
	ds_write_b128 v18, v[208:211]
	ds_write_b128 v18, v[212:215] offset:1024
	ds_write_b128 v18, v[216:219] offset:2048
	ds_write_b128 v18, v[220:223] offset:3072
	s_add_u32 s10, s40, 0x400000
	s_addc_u32 s11, s41, 0
	v_cvt_pk_bf16_f32 v80, v208, v209
	v_cvt_pk_bf16_f32 v81, v210, v211
	v_cvt_pk_bf16_f32 v82, v212, v213
	v_cvt_pk_bf16_f32 v83, v214, v215
	v_cvt_pk_bf16_f32 v84, v216, v217
	v_cvt_pk_bf16_f32 v85, v218, v219
	v_cvt_pk_bf16_f32 v86, v220, v221
	v_cvt_pk_bf16_f32 v87, v222, v223
	global_store_dwordx2 v29, v[80:81], s[10:11]
	global_store_dwordx2 v29, v[82:83], s[10:11] offset:512
	global_store_dwordx2 v29, v[84:85], s[10:11] offset:1024
	global_store_dwordx2 v29, v[86:87], s[10:11] offset:1536
	s_add_u32 s40, s40, 0x800000
	s_addc_u32 s41, s41, 0
	s_waitcnt lgkmcnt(0)
	s_barrier
; #define LAS __attribute__((address_space(3)))
; __device__ __forceinline__ void p0_rows(const Args& a, LAS unsigned char* lds, int gw, int NGW, int wave, int lane, int tid) {
;     ...
;         const int jj = lane & 15, p = lane >> 4; float acc = 0.f;
;         const LAS float* hp = hrow + p * 264; const LAS float* wp = WdL + p * 4112 + jj;
; #pragma unroll 8
;         for (int kk = 0; kk < 256; ++kk) acc += hp[kk] * wp[kk * 16];
;         acc += __shfl_xor(acc, 16); acc += __shfl_xor(acc, 32);
;         if (lane < 16) DLR[(size_t)row * 16 + jj] = acc;
	ds_read_b128 v[128:131], v20
	ds_read_b128 v[132:135], v20 offset:16
	ds_read_b128 v[136:139], v20 offset:32
	ds_read_b128 v[140:143], v20 offset:48
	ds_read_b128 v[144:147], v20 offset:64
	ds_read_b128 v[148:151], v20 offset:80
	ds_read_b128 v[152:155], v20 offset:96
	ds_read_b128 v[156:159], v20 offset:112
	s_waitcnt lgkmcnt(7)
	v_mfma_f32_16x16x4_f32 v[160:163], v128, v96, 0
	v_mfma_f32_16x16x4_f32 v[164:167], v129, v97, 0
	v_mfma_f32_16x16x4_f32 v[160:163], v130, v98, v[160:163]
	v_mfma_f32_16x16x4_f32 v[164:167], v131, v99, v[164:167]
	s_waitcnt lgkmcnt(6)
	v_mfma_f32_16x16x4_f32 v[160:163], v132, v100, v[160:163]
	v_mfma_f32_16x16x4_f32 v[164:167], v133, v101, v[164:167]
	v_mfma_f32_16x16x4_f32 v[160:163], v134, v102, v[160:163]
	v_mfma_f32_16x16x4_f32 v[164:167], v135, v103, v[164:167]
	s_waitcnt lgkmcnt(5)
	v_mfma_f32_16x16x4_f32 v[160:163], v136, v104, v[160:163]
	v_mfma_f32_16x16x4_f32 v[164:167], v137, v105, v[164:167]
	v_mfma_f32_16x16x4_f32 v[160:163], v138, v106, v[160:163]
	v_mfma_f32_16x16x4_f32 v[164:167], v139, v107, v[164:167]
	s_waitcnt lgkmcnt(4)
	v_mfma_f32_16x16x4_f32 v[160:163], v140, v108, v[160:163]
	v_mfma_f32_16x16x4_f32 v[164:167], v141, v109, v[164:167]
	v_mfma_f32_16x16x4_f32 v[160:163], v142, v110, v[160:163]
	v_mfma_f32_16x16x4_f32 v[164:167], v143, v111, v[164:167]
	s_waitcnt lgkmcnt(3)
	v_mfma_f32_16x16x4_f32 v[160:163], v144, v112, v[160:163]
	v_mfma_f32_16x16x4_f32 v[164:167], v145, v113, v[164:167]
	v_mfma_f32_16x16x4_f32 v[160:163], v146, v114, v[160:163]
	v_mfma_f32_16x16x4_f32 v[164:167], v147, v115, v[164:167]
	s_waitcnt lgkmcnt(2)
	v_mfma_f32_16x16x4_f32 v[160:163], v148, v116, v[160:163]
	v_mfma_f32_16x16x4_f32 v[164:167], v149, v117, v[164:167]
	v_mfma_f32_16x16x4_f32 v[160:163], v150, v118, v[160:163]
	v_mfma_f32_16x16x4_f32 v[164:167], v151, v119, v[164:167]
	s_waitcnt lgkmcnt(1)
	v_mfma_f32_16x16x4_f32 v[160:163], v152, v120, v[160:163]
	v_mfma_f32_16x16x4_f32 v[164:167], v153, v121, v[164:167]
	v_mfma_f32_16x16x4_f32 v[160:163], v154, v122, v[160:163]
	v_mfma_f32_16x16x4_f32 v[164:167], v155, v123, v[164:167]
	s_waitcnt lgkmcnt(0)
	v_mfma_f32_16x16x4_f32 v[160:163], v156, v124, v[160:163]
	v_mfma_f32_16x16x4_f32 v[164:167], v157, v125, v[164:167]
	v_mfma_f32_16x16x4_f32 v[160:163], v158, v126, v[160:163]
	v_mfma_f32_16x16x4_f32 v[164:167], v159, v127, v[164:167]
	s_nop 9
	v_add_f32_e32 v160, v160, v164
	v_add_f32_e32 v161, v161, v165
	v_add_f32_e32 v162, v162, v166
	v_add_f32_e32 v163, v163, v167
	ds_write_b128 v21, v[160:163]
	s_waitcnt lgkmcnt(0)
	s_barrier
	s_cmp_lt_u32 s93, 4
	s_cbranch_scc0 .Lp0m_s3skip_b3a
	ds_read_b32 v168, v22
	ds_read_b32 v169, v22 offset:1024
	ds_read_b32 v170, v22 offset:2048
	ds_read_b32 v171, v22 offset:3072
	ds_read_b32 v172, v22 offset:4096
	ds_read_b32 v173, v22 offset:5120
	ds_read_b32 v174, v22 offset:6144
	ds_read_b32 v175, v22 offset:7168
	s_waitcnt lgkmcnt(6)
	v_add_f32_e32 v168, v168, v169
	s_waitcnt lgkmcnt(5)
	v_add_f32_e32 v168, v168, v170
	s_waitcnt lgkmcnt(4)
	v_add_f32_e32 v168, v168, v171
	s_waitcnt lgkmcnt(3)
	v_add_f32_e32 v168, v168, v172
	s_waitcnt lgkmcnt(2)
	v_add_f32_e32 v168, v168, v173
	s_waitcnt lgkmcnt(1)
	v_add_f32_e32 v168, v168, v174
	s_waitcnt lgkmcnt(0)
	v_add_f32_e32 v168, v168, v175
	global_store_dword v23, v168, s[52:53]
